# attention unit epilogue: 16 dwordx2 stores per lane paired with v_permlane32_swap into 8 dwordx4 stores (T21)
# speedup vs baseline: 1.0017x; 1.0017x over previous
; #define LAS __attribute__((address_space(3)))
; __device__ __forceinline__ void attn_unit(const TI ti, CArgs& a, int b, int hd, int qrow0, int st_lo, int st_hi, float mfix, float lam, float lam_init, const float* subg, unsigned char* ldsg) {
;     ...
;     const float ltot = lsum + __shfl_xor(lsum, 32);
;     const float linv = 1.f / ltot;
;     LAS float* X = (LAS float*)L + qt * 4096;
;     if (c == 1) {
; #pragma unroll
;         for (int e = 0; e < 4; ++e)
; #pragma unroll
;             for (int i = 0; i < 16; ++i) X[(e * 16 + i) * 64 + lane] = O[e][i] * linv;
;     }
;     __syncthreads();
;     if (c == 0) {
;         float ssq = 0.f;
; #pragma unroll
;         for (int e = 0; e < 4; ++e)
; #pragma unroll
;             for (int i = 0; i < 16; ++i) { const float o = O[e][i] * linv - lam * X[(e * 16 + i) * 64 + lane]; O[e][i] = o; ssq += o * o; }
.LBB0_346:
	s_or_b64 exec, exec, s[4:5]
	s_waitcnt lgkmcnt(0)
	s_barrier
	s_and_saveexec_b64 s[48:49], s[42:43]
	s_cbranch_execz .LBB0_348
	ds_read2st64_b32 v[90:91], v164 offset1:1
	ds_read2st64_b32 v[92:93], v164 offset0:2 offset1:3
	ds_read2st64_b32 v[94:95], v164 offset0:4 offset1:5
	ds_read2st64_b32 v[96:97], v164 offset0:6 offset1:7
	ds_read2st64_b32 v[98:99], v164 offset0:8 offset1:9
	ds_read2st64_b32 v[104:105], v164 offset0:10 offset1:11
	ds_read2st64_b32 v[108:109], v164 offset0:12 offset1:13
	ds_read2st64_b32 v[110:111], v164 offset0:14 offset1:15
	ds_read2st64_b32 v[112:113], v164 offset0:16 offset1:17
	ds_read2st64_b32 v[114:115], v164 offset0:18 offset1:19
	ds_read2st64_b32 v[116:117], v164 offset0:20 offset1:21
	ds_read2st64_b32 v[118:119], v164 offset0:22 offset1:23
	ds_read2st64_b32 v[120:121], v164 offset0:24 offset1:25
	ds_read2st64_b32 v[122:123], v164 offset0:26 offset1:27
	ds_read2st64_b32 v[124:125], v164 offset0:28 offset1:29
	ds_read2st64_b32 v[126:127], v164 offset0:30 offset1:31
	ds_read2st64_b32 v[128:129], v164 offset0:32 offset1:33
	ds_read2st64_b32 v[130:131], v164 offset0:34 offset1:35
	ds_read2st64_b32 v[132:133], v164 offset0:36 offset1:37
	ds_read2st64_b32 v[182:183], v164 offset0:38 offset1:39
	ds_read2st64_b32 v[184:185], v164 offset0:40 offset1:41
	ds_read2st64_b32 v[198:199], v164 offset0:42 offset1:43
	ds_read2st64_b32 v[200:201], v164 offset0:44 offset1:45
	ds_read2st64_b32 v[202:203], v164 offset0:46 offset1:47
	ds_read2st64_b32 v[204:205], v164 offset0:56 offset1:57
	ds_read2st64_b32 v[206:207], v164 offset0:58 offset1:59
	ds_read2st64_b32 v[82:83], v164 offset0:60 offset1:61
	ds_read2st64_b32 v[84:85], v164 offset0:62 offset1:63
	ds_read2st64_b32 v[208:209], v164 offset0:48 offset1:49
	ds_read2st64_b32 v[210:211], v164 offset0:50 offset1:51
	ds_read2st64_b32 v[212:213], v164 offset0:52 offset1:53
	ds_read2st64_b32 v[214:215], v164 offset0:54 offset1:55
	s_waitcnt lgkmcnt(14)
	v_pk_mul_f32 v[90:91], v[134:135], v[90:91]
	v_pk_mul_f32 v[92:93], v[134:135], v[92:93]
	v_pk_fma_f32 v[90:91], v[18:19], v[86:87], v[90:91] op_sel_hi:[1,0,1] neg_lo:[0,0,1] neg_hi:[0,0,1]
	v_pk_mul_f32 v[18:19], v[134:135], v[96:97]
	v_pk_fma_f32 v[20:21], v[20:21], v[86:87], v[92:93] op_sel_hi:[1,0,1] neg_lo:[0,0,1] neg_hi:[0,0,1]
	v_pk_fma_f32 v[92:93], v[24:25], v[86:87], v[18:19] op_sel_hi:[1,0,1] neg_lo:[0,0,1] neg_hi:[0,0,1]
	v_pk_mul_f32 v[18:19], v[134:135], v[94:95]
	s_waitcnt lgkmcnt(5)
	v_pk_mul_f32 v[82:83], v[134:135], v[82:83]
	v_pk_fma_f32 v[102:103], v[22:23], v[86:87], v[18:19] op_sel_hi:[1,0,1] neg_lo:[0,0,1] neg_hi:[0,0,1]
	v_pk_mul_f32 v[18:19], v[134:135], v[104:105]
	s_waitcnt lgkmcnt(1)
	v_pk_mul_f32 v[22:23], v[134:135], v[212:213]
	v_pk_fma_f32 v[94:95], v[28:29], v[86:87], v[18:19] op_sel_hi:[1,0,1] neg_lo:[0,0,1] neg_hi:[0,0,1]
	v_pk_mul_f32 v[18:19], v[134:135], v[98:99]
	v_pk_fma_f32 v[82:83], v[46:47], v[86:87], v[82:83] op_sel_hi:[1,0,1] neg_lo:[0,0,1] neg_hi:[0,0,1]
	v_pk_fma_f32 v[106:107], v[26:27], v[86:87], v[18:19] op_sel_hi:[1,0,1] neg_lo:[0,0,1] neg_hi:[0,0,1]
	v_pk_mul_f32 v[18:19], v[134:135], v[110:111]
	v_pk_mul_f32 v[46:47], v[134:135], v[84:85]
	v_pk_fma_f32 v[96:97], v[32:33], v[86:87], v[18:19] op_sel_hi:[1,0,1] neg_lo:[0,0,1] neg_hi:[0,0,1]
	v_pk_mul_f32 v[18:19], v[134:135], v[108:109]
	v_pk_mul_f32 v[218:219], v[90:91], v[90:91]
	v_pk_fma_f32 v[108:109], v[30:31], v[86:87], v[18:19] op_sel_hi:[1,0,1] neg_lo:[0,0,1] neg_hi:[0,0,1]
	v_pk_mul_f32 v[18:19], v[134:135], v[114:115]
	v_pk_fma_f32 v[84:85], v[48:49], v[86:87], v[46:47] op_sel_hi:[1,0,1] neg_lo:[0,0,1] neg_hi:[0,0,1]
	v_pk_fma_f32 v[98:99], v[68:69], v[86:87], v[18:19] op_sel_hi:[1,0,1] neg_lo:[0,0,1] neg_hi:[0,0,1]
	v_pk_mul_f32 v[18:19], v[134:135], v[112:113]
	ds_read_b128 v[46:49], v249
	v_pk_fma_f32 v[104:105], v[66:67], v[86:87], v[18:19] op_sel_hi:[1,0,1] neg_lo:[0,0,1] neg_hi:[0,0,1]
	v_pk_mul_f32 v[18:19], v[134:135], v[118:119]
	v_pk_mul_f32 v[216:217], v[20:21], v[20:21]
	v_pk_fma_f32 v[32:33], v[72:73], v[86:87], v[18:19] op_sel_hi:[1,0,1] neg_lo:[0,0,1] neg_hi:[0,0,1]
	v_pk_mul_f32 v[18:19], v[134:135], v[116:117]
	v_pk_mul_f32 v[222:223], v[102:103], v[102:103]
	v_pk_fma_f32 v[70:71], v[70:71], v[86:87], v[18:19] op_sel_hi:[1,0,1] neg_lo:[0,0,1] neg_hi:[0,0,1]
	v_pk_mul_f32 v[18:19], v[134:135], v[122:123]
	v_pk_mul_f32 v[220:221], v[92:93], v[92:93]
	v_pk_fma_f32 v[66:67], v[76:77], v[86:87], v[18:19] op_sel_hi:[1,0,1] neg_lo:[0,0,1] neg_hi:[0,0,1]
	v_pk_mul_f32 v[18:19], v[134:135], v[120:121]
	v_pk_mul_f32 v[226:227], v[106:107], v[106:107]
	v_pk_fma_f32 v[72:73], v[74:75], v[86:87], v[18:19] op_sel_hi:[1,0,1] neg_lo:[0,0,1] neg_hi:[0,0,1]
	v_pk_mul_f32 v[18:19], v[134:135], v[126:127]
	v_pk_mul_f32 v[224:225], v[94:95], v[94:95]
	v_pk_fma_f32 v[68:69], v[80:81], v[86:87], v[18:19] op_sel_hi:[1,0,1] neg_lo:[0,0,1] neg_hi:[0,0,1]
	v_pk_mul_f32 v[18:19], v[134:135], v[124:125]
	v_pk_mul_f32 v[228:229], v[108:109], v[108:109]
	v_pk_fma_f32 v[74:75], v[78:79], v[86:87], v[18:19] op_sel_hi:[1,0,1] neg_lo:[0,0,1] neg_hi:[0,0,1]
	v_pk_mul_f32 v[18:19], v[134:135], v[130:131]
	v_pk_mul_f32 v[110:111], v[96:97], v[96:97]
	v_pk_fma_f32 v[52:53], v[52:53], v[86:87], v[18:19] op_sel_hi:[1,0,1] neg_lo:[0,0,1] neg_hi:[0,0,1]
	v_pk_mul_f32 v[18:19], v[134:135], v[128:129]
	v_pk_mul_f32 v[112:113], v[104:105], v[104:105]
	v_pk_fma_f32 v[50:51], v[50:51], v[86:87], v[18:19] op_sel_hi:[1,0,1] neg_lo:[0,0,1] neg_hi:[0,0,1]
	v_pk_mul_f32 v[18:19], v[134:135], v[182:183]
	v_pk_mul_f32 v[114:115], v[98:99], v[98:99]
	v_pk_fma_f32 v[24:25], v[56:57], v[86:87], v[18:19] op_sel_hi:[1,0,1] neg_lo:[0,0,1] neg_hi:[0,0,1]
; __device__ __forceinline__ unsigned pkbf(float lo, float hi) { f32x2 v = {lo, hi}; bf16x2v b = __builtin_convertvector(v, bf16x2v); return __builtin_bit_cast(unsigned, b); }
; __device__ __forceinline__ void attn_unit(const TI ti, CArgs& a, int b, int hd, int qrow0, int st_lo, int st_hi, float mfix, float lam, float lam_init, const float* subg, unsigned char* ldsg) {
;     ...
;         float ssq = 0.f;
; #pragma unroll
;         for (int e = 0; e < 4; ++e)
; #pragma unroll
;             for (int i = 0; i < 16; ++i) { const float o = O[e][i] * linv - lam * X[(e * 16 + i) * 64 + lane]; O[e][i] = o; ssq += o * o; }
;         ssq += __shfl_xor(ssq, 32);
;         const float sc = rsqrtf(ssq * (1.f / 128.f) + 1e-6f) * (1.f - lam_init);
;         bf16_t* op = Qb + (size_t)(qrow0 + qt * 32 + r) * 1024 + hd * 128;
; #pragma unroll
;         for (int e = 0; e < 4; ++e)
; #pragma unroll
;             for (int g4 = 0; g4 < 4; ++g4) {
;                 const int e0 = e * 32 + 8 * g4 + 4 * h; const f32x4 sg = *(const f32x4*)(subg + e0);
;                 u32x2 o; o.x = pkbf(O[e][4 * g4 + 0] * sc * sg.x, O[e][4 * g4 + 1] * sc * sg.y); o.y = pkbf(O[e][4 * g4 + 2] * sc * sg.z, O[e][4 * g4 + 3] * sc * sg.w);
	v_pk_mul_f32 v[18:19], v[134:135], v[132:133]
	v_pk_mul_f32 v[116:117], v[70:71], v[70:71]
	v_pk_fma_f32 v[54:55], v[54:55], v[86:87], v[18:19] op_sel_hi:[1,0,1] neg_lo:[0,0,1] neg_hi:[0,0,1]
	v_pk_mul_f32 v[18:19], v[134:135], v[198:199]
	v_pk_mul_f32 v[118:119], v[32:33], v[32:33]
	v_pk_fma_f32 v[26:27], v[60:61], v[86:87], v[18:19] op_sel_hi:[1,0,1] neg_lo:[0,0,1] neg_hi:[0,0,1]
	v_pk_mul_f32 v[18:19], v[134:135], v[184:185]
	v_pk_mul_f32 v[120:121], v[72:73], v[72:73]
	v_pk_fma_f32 v[56:57], v[58:59], v[86:87], v[18:19] op_sel_hi:[1,0,1] neg_lo:[0,0,1] neg_hi:[0,0,1]
	v_pk_mul_f32 v[18:19], v[134:135], v[202:203]
	v_pk_mul_f32 v[76:77], v[66:67], v[66:67]
	v_pk_fma_f32 v[28:29], v[64:65], v[86:87], v[18:19] op_sel_hi:[1,0,1] neg_lo:[0,0,1] neg_hi:[0,0,1]
	v_pk_mul_f32 v[18:19], v[134:135], v[200:201]
	v_pk_mul_f32 v[78:79], v[74:75], v[74:75]
	v_pk_fma_f32 v[58:59], v[62:63], v[86:87], v[18:19] op_sel_hi:[1,0,1] neg_lo:[0,0,1] neg_hi:[0,0,1]
	v_pk_mul_f32 v[18:19], v[134:135], v[210:211]
	v_pk_mul_f32 v[80:81], v[68:69], v[68:69]
	v_pk_fma_f32 v[30:31], v[36:37], v[86:87], v[18:19] op_sel_hi:[1,0,1] neg_lo:[0,0,1] neg_hi:[0,0,1]
	v_pk_mul_f32 v[18:19], v[134:135], v[208:209]
	v_pk_fma_f32 v[36:37], v[38:39], v[86:87], v[22:23] op_sel_hi:[1,0,1] neg_lo:[0,0,1] neg_hi:[0,0,1]
	v_pk_fma_f32 v[34:35], v[34:35], v[86:87], v[18:19] op_sel_hi:[1,0,1] neg_lo:[0,0,1] neg_hi:[0,0,1]
	s_waitcnt lgkmcnt(0)
	v_pk_mul_f32 v[18:19], v[134:135], v[214:215]
	v_pk_mul_f32 v[22:23], v[134:135], v[206:207]
	v_pk_mul_f32 v[38:39], v[134:135], v[204:205]
	v_pk_fma_f32 v[18:19], v[40:41], v[86:87], v[18:19] op_sel_hi:[1,0,1] neg_lo:[0,0,1] neg_hi:[0,0,1]
	v_pk_fma_f32 v[22:23], v[44:45], v[86:87], v[22:23] op_sel_hi:[1,0,1] neg_lo:[0,0,1] neg_hi:[0,0,1]
	v_pk_fma_f32 v[38:39], v[42:43], v[86:87], v[38:39] op_sel_hi:[1,0,1] neg_lo:[0,0,1] neg_hi:[0,0,1]
	v_add_f32_e32 v86, v218, v219
	v_add_f32_e32 v86, v86, v216
	v_add_f32_e32 v86, v86, v217
	v_add_f32_e32 v86, v86, v222
	v_add_f32_e32 v86, v86, v223
	v_add_f32_e32 v86, v86, v220
	v_add_f32_e32 v86, v86, v221
	v_add_f32_e32 v86, v86, v226
	v_add_f32_e32 v86, v86, v227
	v_add_f32_e32 v86, v86, v224
	v_add_f32_e32 v86, v86, v225
	v_add_f32_e32 v86, v86, v228
	v_add_f32_e32 v86, v86, v229
	v_add_f32_e32 v86, v86, v110
	v_add_f32_e32 v86, v86, v111
	v_add_f32_e32 v86, v86, v112
	v_add_f32_e32 v86, v86, v113
	v_add_f32_e32 v86, v86, v114
	v_add_f32_e32 v86, v86, v115
	v_add_f32_e32 v86, v86, v116
	v_add_f32_e32 v86, v86, v117
	v_add_f32_e32 v86, v86, v118
	v_add_f32_e32 v86, v86, v119
	v_add_f32_e32 v86, v86, v120
	v_add_f32_e32 v86, v86, v121
	v_add_f32_e32 v76, v86, v76
	v_add_f32_e32 v76, v76, v77
	v_add_f32_e32 v76, v76, v78
	v_add_f32_e32 v76, v76, v79
	v_add_f32_e32 v76, v76, v80
	v_pk_mul_f32 v[124:125], v[50:51], v[50:51]
	v_add_f32_e32 v76, v76, v81
	v_add_f32_e32 v76, v76, v124
	v_pk_mul_f32 v[122:123], v[52:53], v[52:53]
	v_add_f32_e32 v76, v76, v125
	v_add_f32_e32 v76, v76, v122
	v_pk_mul_f32 v[128:129], v[54:55], v[54:55]
	v_add_f32_e32 v76, v76, v123
	v_add_f32_e32 v76, v76, v128
	v_pk_mul_f32 v[126:127], v[24:25], v[24:25]
	v_add_f32_e32 v76, v76, v129
	v_add_f32_e32 v76, v76, v126
	v_pk_mul_f32 v[130:131], v[56:57], v[56:57]
	v_add_f32_e32 v76, v76, v127
	v_add_f32_e32 v76, v76, v130
	v_pk_mul_f32 v[60:61], v[26:27], v[26:27]
	v_add_f32_e32 v76, v76, v131
	v_add_f32_e32 v60, v76, v60
	v_pk_mul_f32 v[62:63], v[58:59], v[58:59]
	v_add_f32_e32 v60, v60, v61
	v_add_f32_e32 v60, v60, v62
	v_pk_mul_f32 v[64:65], v[28:29], v[28:29]
	v_add_f32_e32 v60, v60, v63
	v_add_f32_e32 v60, v60, v64
	v_pk_mul_f32 v[182:183], v[34:35], v[34:35]
	v_add_f32_e32 v60, v60, v65
	v_add_f32_e32 v60, v60, v182
	v_pk_mul_f32 v[132:133], v[30:31], v[30:31]
	v_add_f32_e32 v60, v60, v183
	v_add_f32_e32 v60, v60, v132
	v_pk_mul_f32 v[184:185], v[36:37], v[36:37]
	v_add_f32_e32 v60, v60, v133
	v_add_f32_e32 v60, v60, v184
	v_pk_mul_f32 v[40:41], v[18:19], v[18:19]
	v_add_f32_e32 v60, v60, v185
	v_add_f32_e32 v40, v60, v40
	v_pk_mul_f32 v[42:43], v[38:39], v[38:39]
	v_add_f32_e32 v40, v40, v41
	v_add_f32_e32 v40, v40, v42
	v_pk_mul_f32 v[44:45], v[22:23], v[22:23]
	v_add_f32_e32 v40, v40, v43
	v_add_f32_e32 v40, v40, v44
	v_pk_mul_f32 v[88:89], v[82:83], v[82:83]
	v_add_f32_e32 v40, v40, v45
	v_add_f32_e32 v40, v40, v88
	v_pk_mul_f32 v[100:101], v[84:85], v[84:85]
	v_add_f32_e32 v40, v40, v89
	v_add_f32_e32 v40, v40, v100
	v_add_f32_e32 v40, v40, v101
	ds_bpermute_b32 v41, v137, v40
	s_waitcnt lgkmcnt(0)
	v_add_f32_e32 v40, v40, v41
	v_fmamk_f32 v40, v40, 0x3c000000, v172
	v_mul_f32_e32 v41, 0x4b800000, v40
	v_cmp_gt_f32_e32 vcc, s8, v40
	s_nop 1
	v_cndmask_b32_e32 v40, v40, v41, vcc
	v_rsq_f32_e32 v42, v40
	v_lshlrev_b32_e32 v40, 2, v146
	v_mov_b32_e32 v41, v1
	v_lshl_add_u64 v[44:45], v[152:153], 0, v[40:41]
	v_mul_f32_e32 v40, 0x45800000, v42
	v_cndmask_b32_e32 v40, v42, v40, vcc
	v_mul_f32_e32 v60, v165, v40
	v_pk_mul_f32 v[40:41], v[90:91], v[60:61] op_sel_hi:[1,0]
	v_pk_mul_f32 v[20:21], v[20:21], v[60:61] op_sel_hi:[1,0]
	s_waitcnt lgkmcnt(0)
	v_pk_mul_f32 v[40:41], v[46:47], v[40:41]
	v_pk_mul_f32 v[20:21], v[48:49], v[20:21]
	v_cvt_pk_bf16_f32 v250, v40, v41
	v_cvt_pk_bf16_f32 v251, v20, v21
	ds_read_b128 v[40:43], v249 offset:32
	v_pk_mul_f32 v[20:21], v[102:103], v[60:61] op_sel_hi:[1,0]
	v_pk_mul_f32 v[46:47], v[94:95], v[60:61] op_sel_hi:[1,0]
	v_pk_mul_f32 v[32:33], v[32:33], v[60:61] op_sel_hi:[1,0]
	v_pk_mul_f32 v[24:25], v[24:25], v[60:61] op_sel_hi:[1,0]
	v_pk_mul_f32 v[28:29], v[28:29], v[60:61] op_sel_hi:[1,0]
	v_pk_mul_f32 v[18:19], v[18:19], v[60:61] op_sel_hi:[1,0]
	v_pk_mul_f32 v[22:23], v[22:23], v[60:61] op_sel_hi:[1,0]
	s_waitcnt lgkmcnt(0)
; __device__ __forceinline__ unsigned pkbf(float lo, float hi) { f32x2 v = {lo, hi}; bf16x2v b = __builtin_convertvector(v, bf16x2v); return __builtin_bit_cast(unsigned, b); }
; __device__ __forceinline__ void attn_unit(const TI ti, CArgs& a, int b, int hd, int qrow0, int st_lo, int st_hi, float mfix, float lam, float lam_init, const float* subg, unsigned char* ldsg) {
;     ...
; #pragma unroll
;         for (int e = 0; e < 4; ++e)
; #pragma unroll
;             for (int g4 = 0; g4 < 4; ++g4) {
;                 const int e0 = e * 32 + 8 * g4 + 4 * h; const f32x4 sg = *(const f32x4*)(subg + e0);
;                 u32x2 o; o.x = pkbf(O[e][4 * g4 + 0] * sc * sg.x, O[e][4 * g4 + 1] * sc * sg.y); o.y = pkbf(O[e][4 * g4 + 2] * sc * sg.z, O[e][4 * g4 + 3] * sc * sg.w);
;                 *(u32x2*)(op + e0) = o;
;             }
	v_pk_mul_f32 v[20:21], v[40:41], v[20:21]
	v_pk_mul_f32 v[40:41], v[92:93], v[60:61] op_sel_hi:[1,0]
	v_cvt_pk_bf16_f32 v252, v20, v21
	v_pk_mul_f32 v[40:41], v[42:43], v[40:41]
	s_nop 0
	v_cvt_pk_bf16_f32 v253, v40, v41
	s_nop 1
	v_permlane32_swap_b32 v250, v252
	v_permlane32_swap_b32 v251, v253
	s_nop 0
	global_store_dwordx4 v[44:45], v[250:253], off
	ds_read_b128 v[40:43], v249 offset:64
	v_pk_mul_f32 v[20:21], v[106:107], v[60:61] op_sel_hi:[1,0]
	s_waitcnt lgkmcnt(0)
	v_pk_mul_f32 v[20:21], v[40:41], v[20:21]
	v_pk_mul_f32 v[40:41], v[42:43], v[46:47]
	v_cvt_pk_bf16_f32 v250, v20, v21
	v_cvt_pk_bf16_f32 v251, v40, v41
	ds_read_b128 v[40:43], v249 offset:96
	v_pk_mul_f32 v[20:21], v[108:109], v[60:61] op_sel_hi:[1,0]
	v_pk_mul_f32 v[46:47], v[96:97], v[60:61] op_sel_hi:[1,0]
	s_waitcnt lgkmcnt(0)
	v_pk_mul_f32 v[20:21], v[40:41], v[20:21]
	v_pk_mul_f32 v[40:41], v[42:43], v[46:47]
	v_cvt_pk_bf16_f32 v252, v20, v21
	v_cvt_pk_bf16_f32 v253, v40, v41
	s_nop 1
	v_permlane32_swap_b32 v250, v252
	v_permlane32_swap_b32 v251, v253
	s_nop 0
	global_store_dwordx4 v[44:45], v[250:253], off offset:32
	ds_read_b128 v[40:43], v249 offset:128
	v_pk_mul_f32 v[20:21], v[104:105], v[60:61] op_sel_hi:[1,0]
	v_pk_mul_f32 v[46:47], v[98:99], v[60:61] op_sel_hi:[1,0]
	s_waitcnt lgkmcnt(0)
	v_pk_mul_f32 v[20:21], v[40:41], v[20:21]
	v_pk_mul_f32 v[40:41], v[42:43], v[46:47]
	v_cvt_pk_bf16_f32 v250, v20, v21
	v_cvt_pk_bf16_f32 v251, v40, v41
	ds_read_b128 v[40:43], v249 offset:160
	v_pk_mul_f32 v[20:21], v[70:71], v[60:61] op_sel_hi:[1,0]
	s_waitcnt lgkmcnt(0)
	v_pk_mul_f32 v[32:33], v[42:43], v[32:33]
	v_pk_mul_f32 v[20:21], v[40:41], v[20:21]
	s_nop 0
	v_cvt_pk_bf16_f32 v252, v20, v21
	v_cvt_pk_bf16_f32 v253, v32, v33
	s_nop 1
	v_permlane32_swap_b32 v250, v252
	v_permlane32_swap_b32 v251, v253
	s_nop 0
	global_store_dwordx4 v[44:45], v[250:253], off offset:64
	ds_read_b128 v[40:43], v249 offset:192
	v_pk_mul_f32 v[20:21], v[72:73], v[60:61] op_sel_hi:[1,0]
	v_pk_mul_f32 v[32:33], v[66:67], v[60:61] op_sel_hi:[1,0]
	s_waitcnt lgkmcnt(0)
	v_pk_mul_f32 v[20:21], v[40:41], v[20:21]
	v_pk_mul_f32 v[32:33], v[42:43], v[32:33]
	v_cvt_pk_bf16_f32 v250, v20, v21
	v_cvt_pk_bf16_f32 v251, v32, v33
	ds_read_b128 v[40:43], v249 offset:224
	v_pk_mul_f32 v[20:21], v[74:75], v[60:61] op_sel_hi:[1,0]
	v_pk_mul_f32 v[32:33], v[68:69], v[60:61] op_sel_hi:[1,0]
	s_waitcnt lgkmcnt(0)
	v_pk_mul_f32 v[20:21], v[20:21], v[40:41]
	v_pk_mul_f32 v[32:33], v[32:33], v[42:43]
	v_cvt_pk_bf16_f32 v252, v20, v21
	v_cvt_pk_bf16_f32 v253, v32, v33
	s_nop 1
	v_permlane32_swap_b32 v250, v252
	v_permlane32_swap_b32 v251, v253
	s_nop 0
	global_store_dwordx4 v[44:45], v[250:253], off offset:96
	ds_read_b128 v[40:43], v249 offset:256
	v_pk_mul_f32 v[20:21], v[50:51], v[60:61] op_sel_hi:[1,0]
	v_pk_mul_f32 v[32:33], v[52:53], v[60:61] op_sel_hi:[1,0]
	s_waitcnt lgkmcnt(0)
	v_pk_mul_f32 v[20:21], v[20:21], v[40:41]
	v_pk_mul_f32 v[32:33], v[32:33], v[42:43]
	v_cvt_pk_bf16_f32 v250, v20, v21
	v_cvt_pk_bf16_f32 v251, v32, v33
	ds_read_b128 v[40:43], v249 offset:288
	v_pk_mul_f32 v[20:21], v[54:55], v[60:61] op_sel_hi:[1,0]
	s_waitcnt lgkmcnt(0)
	v_pk_mul_f32 v[24:25], v[24:25], v[42:43]
	v_pk_mul_f32 v[20:21], v[20:21], v[40:41]
	s_nop 0
	v_cvt_pk_bf16_f32 v252, v20, v21
	v_cvt_pk_bf16_f32 v253, v24, v25
	s_nop 1
	v_permlane32_swap_b32 v250, v252
	v_permlane32_swap_b32 v251, v253
	s_nop 0
	global_store_dwordx4 v[44:45], v[250:253], off offset:128
	ds_read_b128 v[40:43], v249 offset:320
	v_pk_mul_f32 v[20:21], v[56:57], v[60:61] op_sel_hi:[1,0]
	v_pk_mul_f32 v[24:25], v[26:27], v[60:61] op_sel_hi:[1,0]
	s_waitcnt lgkmcnt(0)
	v_pk_mul_f32 v[20:21], v[20:21], v[40:41]
	v_pk_mul_f32 v[24:25], v[24:25], v[42:43]
	v_cvt_pk_bf16_f32 v250, v20, v21
	v_cvt_pk_bf16_f32 v251, v24, v25
	ds_read_b128 v[24:27], v249 offset:352
	v_pk_mul_f32 v[20:21], v[58:59], v[60:61] op_sel_hi:[1,0]
	s_waitcnt lgkmcnt(0)
	v_pk_mul_f32 v[20:21], v[20:21], v[24:25]
	v_pk_mul_f32 v[24:25], v[28:29], v[26:27]
	v_cvt_pk_bf16_f32 v252, v20, v21
	v_cvt_pk_bf16_f32 v253, v24, v25
	s_nop 1
	v_permlane32_swap_b32 v250, v252
	v_permlane32_swap_b32 v251, v253
	s_nop 0
	global_store_dwordx4 v[44:45], v[250:253], off offset:160
	ds_read_b128 v[24:27], v249 offset:384
	v_pk_mul_f32 v[20:21], v[34:35], v[60:61] op_sel_hi:[1,0]
	v_pk_mul_f32 v[28:29], v[30:31], v[60:61] op_sel_hi:[1,0]
	s_waitcnt lgkmcnt(0)
	v_pk_mul_f32 v[20:21], v[20:21], v[24:25]
	v_pk_mul_f32 v[24:25], v[28:29], v[26:27]
	v_cvt_pk_bf16_f32 v250, v20, v21
	v_cvt_pk_bf16_f32 v251, v24, v25
	ds_read_b128 v[24:27], v249 offset:416
	v_pk_mul_f32 v[20:21], v[36:37], v[60:61] op_sel_hi:[1,0]
	s_waitcnt lgkmcnt(0)
	v_pk_mul_f32 v[18:19], v[18:19], v[26:27]
	v_pk_mul_f32 v[20:21], v[20:21], v[24:25]
	v_pk_mul_f32 v[24:25], v[38:39], v[60:61] op_sel_hi:[1,0]
	v_cvt_pk_bf16_f32 v252, v20, v21
	v_cvt_pk_bf16_f32 v253, v18, v19
	s_nop 1
	v_permlane32_swap_b32 v250, v252
	v_permlane32_swap_b32 v251, v253
	s_nop 0
	global_store_dwordx4 v[44:45], v[250:253], off offset:192
	ds_read_b128 v[18:21], v249 offset:448
	s_waitcnt lgkmcnt(0)
	v_pk_mul_f32 v[18:19], v[24:25], v[18:19]
	v_pk_mul_f32 v[20:21], v[22:23], v[20:21]
	v_cvt_pk_bf16_f32 v250, v18, v19
	v_cvt_pk_bf16_f32 v251, v20, v21
	ds_read_b128 v[18:21], v249 offset:480
	v_pk_mul_f32 v[22:23], v[82:83], v[60:61] op_sel_hi:[1,0]
	v_pk_mul_f32 v[24:25], v[84:85], v[60:61] op_sel_hi:[1,0]
	s_waitcnt lgkmcnt(0)
	v_pk_mul_f32 v[18:19], v[22:23], v[18:19]
	v_pk_mul_f32 v[20:21], v[24:25], v[20:21]
	v_cvt_pk_bf16_f32 v252, v18, v19
	v_cvt_pk_bf16_f32 v253, v20, v21
	s_nop 1
	v_permlane32_swap_b32 v250, v252
	v_permlane32_swap_b32 v251, v253
	s_nop 0
	global_store_dwordx4 v[44:45], v[250:253], off offset:224

; __device__ __forceinline__ void attn_unit(const TI ti, CArgs& a, int b, int hd, int qrow0, int st_lo, int st_hi, float mfix, float lam, float lam_init, const float* subg, unsigned char* ldsg) {
;     ...
;     if (c == 0) {
;         float ssq = 0.f;
; #pragma unroll
;         for (int e = 0; e < 4; ++e)
; #pragma unroll
;             for (int i = 0; i < 16; ++i) { const float o = O[e][i] * linv - lam * X[(e * 16 + i) * 64 + lane]; O[e][i] = o; ssq += o * o; }
.LBB0_362:
	s_or_b64 exec, exec, s[4:5]
	s_waitcnt lgkmcnt(0)
	s_barrier
	s_and_saveexec_b64 s[48:49], s[42:43]
	s_cbranch_execz .LBB0_331
	ds_read2st64_b32 v[88:89], v164 offset1:1
	ds_read2st64_b32 v[90:91], v164 offset0:2 offset1:3
	ds_read2st64_b32 v[92:93], v164 offset0:4 offset1:5
	ds_read2st64_b32 v[94:95], v164 offset0:6 offset1:7
	ds_read2st64_b32 v[96:97], v164 offset0:8 offset1:9
	ds_read2st64_b32 v[102:103], v164 offset0:10 offset1:11
	ds_read2st64_b32 v[104:105], v164 offset0:12 offset1:13
	ds_read2st64_b32 v[106:107], v164 offset0:14 offset1:15
	ds_read2st64_b32 v[108:109], v164 offset0:16 offset1:17
	ds_read2st64_b32 v[114:115], v164 offset0:18 offset1:19
	ds_read2st64_b32 v[116:117], v164 offset0:20 offset1:21
	ds_read2st64_b32 v[118:119], v164 offset0:22 offset1:23
	ds_read2st64_b32 v[120:121], v164 offset0:24 offset1:25
	ds_read2st64_b32 v[122:123], v164 offset0:26 offset1:27
	ds_read2st64_b32 v[124:125], v164 offset0:28 offset1:29
	ds_read2st64_b32 v[126:127], v164 offset0:30 offset1:31
	ds_read2st64_b32 v[128:129], v164 offset0:32 offset1:33
	ds_read2st64_b32 v[130:131], v164 offset0:34 offset1:35
	ds_read2st64_b32 v[132:133], v164 offset0:36 offset1:37
	ds_read2st64_b32 v[150:151], v164 offset0:38 offset1:39
	ds_read2st64_b32 v[170:171], v164 offset0:40 offset1:41
	ds_read2st64_b32 v[182:183], v164 offset0:42 offset1:43
	ds_read2st64_b32 v[184:185], v164 offset0:44 offset1:45
	ds_read2st64_b32 v[198:199], v164 offset0:46 offset1:47
	ds_read2st64_b32 v[200:201], v164 offset0:56 offset1:57
	ds_read2st64_b32 v[202:203], v164 offset0:58 offset1:59
	ds_read2st64_b32 v[82:83], v164 offset0:60 offset1:61
	ds_read2st64_b32 v[84:85], v164 offset0:62 offset1:63
	ds_read2st64_b32 v[204:205], v164 offset0:48 offset1:49
	ds_read2st64_b32 v[206:207], v164 offset0:50 offset1:51
	ds_read2st64_b32 v[208:209], v164 offset0:52 offset1:53
	ds_read2st64_b32 v[210:211], v164 offset0:54 offset1:55
	s_waitcnt lgkmcnt(14)
	v_pk_mul_f32 v[88:89], v[134:135], v[88:89]
	v_pk_mul_f32 v[90:91], v[134:135], v[90:91]
	v_pk_fma_f32 v[88:89], v[18:19], v[0:1], v[88:89] op_sel_hi:[1,0,1] neg_lo:[0,0,1] neg_hi:[0,0,1]
	v_pk_mul_f32 v[18:19], v[134:135], v[94:95]
	v_pk_fma_f32 v[20:21], v[20:21], v[0:1], v[90:91] op_sel_hi:[1,0,1] neg_lo:[0,0,1] neg_hi:[0,0,1]
	v_pk_fma_f32 v[90:91], v[24:25], v[0:1], v[18:19] op_sel_hi:[1,0,1] neg_lo:[0,0,1] neg_hi:[0,0,1]
	v_pk_mul_f32 v[18:19], v[134:135], v[92:93]
	s_waitcnt lgkmcnt(5)
	v_pk_mul_f32 v[82:83], v[134:135], v[82:83]
	v_pk_fma_f32 v[100:101], v[22:23], v[0:1], v[18:19] op_sel_hi:[1,0,1] neg_lo:[0,0,1] neg_hi:[0,0,1]
	v_pk_mul_f32 v[18:19], v[134:135], v[102:103]
	s_waitcnt lgkmcnt(1)
	v_pk_mul_f32 v[22:23], v[134:135], v[208:209]
	v_pk_fma_f32 v[92:93], v[28:29], v[0:1], v[18:19] op_sel_hi:[1,0,1] neg_lo:[0,0,1] neg_hi:[0,0,1]
	v_pk_mul_f32 v[18:19], v[134:135], v[96:97]
	v_pk_fma_f32 v[82:83], v[62:63], v[0:1], v[82:83] op_sel_hi:[1,0,1] neg_lo:[0,0,1] neg_hi:[0,0,1]
	v_pk_fma_f32 v[110:111], v[26:27], v[0:1], v[18:19] op_sel_hi:[1,0,1] neg_lo:[0,0,1] neg_hi:[0,0,1]
	v_pk_mul_f32 v[18:19], v[134:135], v[106:107]
	v_pk_mul_f32 v[62:63], v[134:135], v[84:85]
	v_pk_fma_f32 v[94:95], v[32:33], v[0:1], v[18:19] op_sel_hi:[1,0,1] neg_lo:[0,0,1] neg_hi:[0,0,1]
	v_pk_mul_f32 v[18:19], v[134:135], v[104:105]
	v_pk_mul_f32 v[214:215], v[88:89], v[88:89]
	v_pk_fma_f32 v[112:113], v[30:31], v[0:1], v[18:19] op_sel_hi:[1,0,1] neg_lo:[0,0,1] neg_hi:[0,0,1]
	v_pk_mul_f32 v[18:19], v[134:135], v[114:115]
	v_pk_fma_f32 v[84:85], v[64:65], v[0:1], v[62:63] op_sel_hi:[1,0,1] neg_lo:[0,0,1] neg_hi:[0,0,1]
	v_pk_fma_f32 v[96:97], v[36:37], v[0:1], v[18:19] op_sel_hi:[1,0,1] neg_lo:[0,0,1] neg_hi:[0,0,1]
	v_pk_mul_f32 v[18:19], v[134:135], v[108:109]
	ds_read_b128 v[62:65], v249
	v_pk_fma_f32 v[102:103], v[34:35], v[0:1], v[18:19] op_sel_hi:[1,0,1] neg_lo:[0,0,1] neg_hi:[0,0,1]
	v_pk_mul_f32 v[18:19], v[134:135], v[118:119]
	v_pk_mul_f32 v[212:213], v[20:21], v[20:21]
	v_pk_fma_f32 v[32:33], v[40:41], v[0:1], v[18:19] op_sel_hi:[1,0,1] neg_lo:[0,0,1] neg_hi:[0,0,1]
	v_pk_mul_f32 v[18:19], v[134:135], v[116:117]
	v_pk_mul_f32 v[218:219], v[100:101], v[100:101]
	v_pk_fma_f32 v[104:105], v[38:39], v[0:1], v[18:19] op_sel_hi:[1,0,1] neg_lo:[0,0,1] neg_hi:[0,0,1]
	v_pk_mul_f32 v[18:19], v[134:135], v[122:123]
	v_pk_mul_f32 v[216:217], v[90:91], v[90:91]
	v_pk_fma_f32 v[34:35], v[44:45], v[0:1], v[18:19] op_sel_hi:[1,0,1] neg_lo:[0,0,1] neg_hi:[0,0,1]
	v_pk_mul_f32 v[18:19], v[134:135], v[120:121]
	v_pk_mul_f32 v[44:45], v[134:135], v[200:201]
	v_pk_fma_f32 v[106:107], v[42:43], v[0:1], v[18:19] op_sel_hi:[1,0,1] neg_lo:[0,0,1] neg_hi:[0,0,1]
	v_pk_mul_f32 v[18:19], v[134:135], v[126:127]
	v_pk_fma_f32 v[42:43], v[54:55], v[0:1], v[22:23] op_sel_hi:[1,0,1] neg_lo:[0,0,1] neg_hi:[0,0,1]
	v_pk_fma_f32 v[36:37], v[48:49], v[0:1], v[18:19] op_sel_hi:[1,0,1] neg_lo:[0,0,1] neg_hi:[0,0,1]
	v_pk_mul_f32 v[18:19], v[134:135], v[124:125]
	v_pk_mul_f32 v[22:23], v[134:135], v[202:203]
	v_pk_fma_f32 v[108:109], v[46:47], v[0:1], v[18:19] op_sel_hi:[1,0,1] neg_lo:[0,0,1] neg_hi:[0,0,1]
	v_pk_mul_f32 v[18:19], v[134:135], v[130:131]
	v_pk_fma_f32 v[22:23], v[60:61], v[0:1], v[22:23] op_sel_hi:[1,0,1] neg_lo:[0,0,1] neg_hi:[0,0,1]
	v_pk_fma_f32 v[38:39], v[68:69], v[0:1], v[18:19] op_sel_hi:[1,0,1] neg_lo:[0,0,1] neg_hi:[0,0,1]
	v_pk_mul_f32 v[18:19], v[134:135], v[128:129]
	v_pk_fma_f32 v[44:45], v[58:59], v[0:1], v[44:45] op_sel_hi:[1,0,1] neg_lo:[0,0,1] neg_hi:[0,0,1]
	v_pk_fma_f32 v[46:47], v[66:67], v[0:1], v[18:19] op_sel_hi:[1,0,1] neg_lo:[0,0,1] neg_hi:[0,0,1]
	v_pk_mul_f32 v[18:19], v[134:135], v[150:151]
	v_pk_mul_f32 v[222:223], v[110:111], v[110:111]
; __device__ __forceinline__ unsigned pkbf(float lo, float hi) { f32x2 v = {lo, hi}; bf16x2v b = __builtin_convertvector(v, bf16x2v); return __builtin_bit_cast(unsigned, b); }
; __device__ __forceinline__ void attn_unit(const TI ti, CArgs& a, int b, int hd, int qrow0, int st_lo, int st_hi, float mfix, float lam, float lam_init, const float* subg, unsigned char* ldsg) {
;     ...
;         float ssq = 0.f;
; #pragma unroll
;         for (int e = 0; e < 4; ++e)
; #pragma unroll
;             for (int i = 0; i < 16; ++i) { const float o = O[e][i] * linv - lam * X[(e * 16 + i) * 64 + lane]; O[e][i] = o; ssq += o * o; }
;         ssq += __shfl_xor(ssq, 32);
;         const float sc = rsqrtf(ssq * (1.f / 128.f) + 1e-6f) * (1.f - lam_init);
;         bf16_t* op = Qb + (size_t)(qrow0 + qt * 32 + r) * 1024 + hd * 128;
; #pragma unroll
;         for (int e = 0; e < 4; ++e)
; #pragma unroll
;             for (int g4 = 0; g4 < 4; ++g4) {
;                 const int e0 = e * 32 + 8 * g4 + 4 * h; const f32x4 sg = *(const f32x4*)(subg + e0);
;                 u32x2 o; o.x = pkbf(O[e][4 * g4 + 0] * sc * sg.x, O[e][4 * g4 + 1] * sc * sg.y); o.y = pkbf(O[e][4 * g4 + 2] * sc * sg.z, O[e][4 * g4 + 3] * sc * sg.w);
	v_pk_fma_f32 v[24:25], v[72:73], v[0:1], v[18:19] op_sel_hi:[1,0,1] neg_lo:[0,0,1] neg_hi:[0,0,1]
	v_pk_mul_f32 v[18:19], v[134:135], v[132:133]
	v_pk_mul_f32 v[220:221], v[92:93], v[92:93]
	v_pk_fma_f32 v[48:49], v[70:71], v[0:1], v[18:19] op_sel_hi:[1,0,1] neg_lo:[0,0,1] neg_hi:[0,0,1]
	v_pk_mul_f32 v[18:19], v[134:135], v[182:183]
	v_pk_mul_f32 v[226:227], v[112:113], v[112:113]
	v_pk_fma_f32 v[26:27], v[76:77], v[0:1], v[18:19] op_sel_hi:[1,0,1] neg_lo:[0,0,1] neg_hi:[0,0,1]
	v_pk_mul_f32 v[18:19], v[134:135], v[170:171]
	v_pk_mul_f32 v[224:225], v[94:95], v[94:95]
	v_pk_fma_f32 v[66:67], v[74:75], v[0:1], v[18:19] op_sel_hi:[1,0,1] neg_lo:[0,0,1] neg_hi:[0,0,1]
	v_pk_mul_f32 v[18:19], v[134:135], v[198:199]
	v_pk_mul_f32 v[228:229], v[102:103], v[102:103]
	v_pk_fma_f32 v[28:29], v[80:81], v[0:1], v[18:19] op_sel_hi:[1,0,1] neg_lo:[0,0,1] neg_hi:[0,0,1]
	v_pk_mul_f32 v[18:19], v[134:135], v[184:185]
	v_pk_mul_f32 v[114:115], v[96:97], v[96:97]
	v_pk_fma_f32 v[68:69], v[78:79], v[0:1], v[18:19] op_sel_hi:[1,0,1] neg_lo:[0,0,1] neg_hi:[0,0,1]
	v_pk_mul_f32 v[18:19], v[134:135], v[206:207]
	v_pk_mul_f32 v[116:117], v[104:105], v[104:105]
	v_pk_fma_f32 v[30:31], v[52:53], v[0:1], v[18:19] op_sel_hi:[1,0,1] neg_lo:[0,0,1] neg_hi:[0,0,1]
	v_pk_mul_f32 v[18:19], v[134:135], v[204:205]
	v_pk_mul_f32 v[118:119], v[32:33], v[32:33]
	v_pk_fma_f32 v[40:41], v[50:51], v[0:1], v[18:19] op_sel_hi:[1,0,1] neg_lo:[0,0,1] neg_hi:[0,0,1]
	s_waitcnt lgkmcnt(0)
	v_pk_mul_f32 v[18:19], v[134:135], v[210:211]
	v_pk_mul_f32 v[120:121], v[106:107], v[106:107]
	v_pk_fma_f32 v[18:19], v[56:57], v[0:1], v[18:19] op_sel_hi:[1,0,1] neg_lo:[0,0,1] neg_hi:[0,0,1]
	v_add_f32_e32 v0, v214, v215
	v_add_f32_e32 v0, v0, v212
	v_add_f32_e32 v0, v0, v213
	v_add_f32_e32 v0, v0, v218
	v_add_f32_e32 v0, v0, v219
	v_add_f32_e32 v0, v0, v216
	v_add_f32_e32 v0, v0, v217
	v_add_f32_e32 v0, v0, v222
	v_add_f32_e32 v0, v0, v223
	v_add_f32_e32 v0, v0, v220
	v_add_f32_e32 v0, v0, v221
	v_add_f32_e32 v0, v0, v226
	v_add_f32_e32 v0, v0, v227
	v_add_f32_e32 v0, v0, v224
	v_add_f32_e32 v0, v0, v225
	v_add_f32_e32 v0, v0, v228
	v_add_f32_e32 v0, v0, v229
	v_add_f32_e32 v0, v0, v114
	v_add_f32_e32 v0, v0, v115
	v_add_f32_e32 v0, v0, v116
	v_add_f32_e32 v0, v0, v117
	v_add_f32_e32 v0, v0, v118
	v_add_f32_e32 v0, v0, v119
	v_add_f32_e32 v0, v0, v120
	v_pk_mul_f32 v[122:123], v[34:35], v[34:35]
	v_add_f32_e32 v0, v0, v121
	v_add_f32_e32 v0, v0, v122
	v_pk_mul_f32 v[124:125], v[108:109], v[108:109]
	v_add_f32_e32 v0, v0, v123
	v_add_f32_e32 v0, v0, v124
	v_pk_mul_f32 v[126:127], v[36:37], v[36:37]
	v_add_f32_e32 v0, v0, v125
	v_add_f32_e32 v0, v0, v126
	v_pk_mul_f32 v[128:129], v[46:47], v[46:47]
	v_add_f32_e32 v0, v0, v127
	v_add_f32_e32 v0, v0, v128
	v_pk_mul_f32 v[130:131], v[38:39], v[38:39]
	v_add_f32_e32 v0, v0, v129
	v_add_f32_e32 v0, v0, v130
	v_pk_mul_f32 v[70:71], v[48:49], v[48:49]
	v_add_f32_e32 v0, v0, v131
	v_add_f32_e32 v0, v0, v70
	v_pk_mul_f32 v[72:73], v[24:25], v[24:25]
	v_add_f32_e32 v0, v0, v71
	v_add_f32_e32 v0, v0, v72
	v_pk_mul_f32 v[74:75], v[66:67], v[66:67]
	v_add_f32_e32 v0, v0, v73
	v_add_f32_e32 v0, v0, v74
	v_pk_mul_f32 v[76:77], v[26:27], v[26:27]
	v_add_f32_e32 v0, v0, v75
	v_add_f32_e32 v0, v0, v76
	v_pk_mul_f32 v[78:79], v[68:69], v[68:69]
	v_add_f32_e32 v0, v0, v77
	v_add_f32_e32 v0, v0, v78
	v_pk_mul_f32 v[80:81], v[28:29], v[28:29]
	v_add_f32_e32 v0, v0, v79
	v_add_f32_e32 v0, v0, v80
	v_pk_mul_f32 v[50:51], v[40:41], v[40:41]
	v_add_f32_e32 v0, v0, v81
	v_add_f32_e32 v0, v0, v50
	v_pk_mul_f32 v[52:53], v[30:31], v[30:31]
	v_add_f32_e32 v0, v0, v51
	v_add_f32_e32 v0, v0, v52
	v_pk_mul_f32 v[54:55], v[42:43], v[42:43]
	v_add_f32_e32 v0, v0, v53
	v_add_f32_e32 v0, v0, v54
	v_pk_mul_f32 v[56:57], v[18:19], v[18:19]
	v_add_f32_e32 v0, v0, v55
	v_add_f32_e32 v0, v0, v56
	v_pk_mul_f32 v[58:59], v[44:45], v[44:45]
	v_add_f32_e32 v0, v0, v57
	v_add_f32_e32 v0, v0, v58
	v_pk_mul_f32 v[60:61], v[22:23], v[22:23]
	v_add_f32_e32 v0, v0, v59
	v_add_f32_e32 v0, v0, v60
	v_pk_mul_f32 v[86:87], v[82:83], v[82:83]
	v_add_f32_e32 v0, v0, v61
	v_add_f32_e32 v0, v0, v86
	v_pk_mul_f32 v[98:99], v[84:85], v[84:85]
	v_add_f32_e32 v0, v0, v87
	v_add_f32_e32 v0, v0, v98
	v_add_f32_e32 v0, v0, v99
	ds_bpermute_b32 v50, v137, v0
	s_waitcnt lgkmcnt(0)
	v_add_f32_e32 v0, v0, v50
	v_fmamk_f32 v0, v0, 0x3c000000, v172
	v_mul_f32_e32 v50, 0x4b800000, v0
	v_cmp_gt_f32_e32 vcc, s8, v0
	s_nop 1
	v_cndmask_b32_e32 v0, v0, v50, vcc
	v_rsq_f32_e32 v50, v0
	v_lshlrev_b32_e32 v0, 2, v146
	v_lshl_add_u64 v[54:55], v[152:153], 0, v[0:1]
	v_mul_f32_e32 v0, 0x45800000, v50
	v_cndmask_b32_e32 v0, v50, v0, vcc
	v_mul_f32_e32 v0, v165, v0
	v_pk_mul_f32 v[50:51], v[88:89], v[0:1] op_sel_hi:[1,0]
	v_pk_mul_f32 v[20:21], v[20:21], v[0:1] op_sel_hi:[1,0]
	s_waitcnt lgkmcnt(0)
	v_pk_mul_f32 v[50:51], v[62:63], v[50:51]
	v_pk_mul_f32 v[20:21], v[64:65], v[20:21]
	v_cvt_pk_bf16_f32 v250, v50, v51
	v_cvt_pk_bf16_f32 v251, v20, v21
	ds_read_b128 v[50:53], v249 offset:32
	v_pk_mul_f32 v[20:21], v[100:101], v[0:1] op_sel_hi:[1,0]
	v_pk_mul_f32 v[56:57], v[92:93], v[0:1] op_sel_hi:[1,0]
	v_pk_mul_f32 v[32:33], v[32:33], v[0:1] op_sel_hi:[1,0]
	v_pk_mul_f32 v[36:37], v[36:37], v[0:1] op_sel_hi:[1,0]
	v_pk_mul_f32 v[24:25], v[24:25], v[0:1] op_sel_hi:[1,0]
	v_pk_mul_f32 v[28:29], v[28:29], v[0:1] op_sel_hi:[1,0]
	v_pk_mul_f32 v[18:19], v[18:19], v[0:1] op_sel_hi:[1,0]
	v_pk_mul_f32 v[22:23], v[22:23], v[0:1] op_sel_hi:[1,0]
	s_waitcnt lgkmcnt(0)
; __device__ __forceinline__ unsigned pkbf(float lo, float hi) { f32x2 v = {lo, hi}; bf16x2v b = __builtin_convertvector(v, bf16x2v); return __builtin_bit_cast(unsigned, b); }
; __device__ __forceinline__ void attn_unit(const TI ti, CArgs& a, int b, int hd, int qrow0, int st_lo, int st_hi, float mfix, float lam, float lam_init, const float* subg, unsigned char* ldsg) {
;     ...
; #pragma unroll
;         for (int e = 0; e < 4; ++e)
; #pragma unroll
;             for (int g4 = 0; g4 < 4; ++g4) {
;                 const int e0 = e * 32 + 8 * g4 + 4 * h; const f32x4 sg = *(const f32x4*)(subg + e0);
;                 u32x2 o; o.x = pkbf(O[e][4 * g4 + 0] * sc * sg.x, O[e][4 * g4 + 1] * sc * sg.y); o.y = pkbf(O[e][4 * g4 + 2] * sc * sg.z, O[e][4 * g4 + 3] * sc * sg.w);
;                 *(u32x2*)(op + e0) = o;
;             }
	v_pk_mul_f32 v[20:21], v[50:51], v[20:21]
	v_pk_mul_f32 v[50:51], v[90:91], v[0:1] op_sel_hi:[1,0]
	v_cvt_pk_bf16_f32 v252, v20, v21
	v_pk_mul_f32 v[50:51], v[52:53], v[50:51]
	s_nop 0
	v_cvt_pk_bf16_f32 v253, v50, v51
	s_nop 1
	v_permlane32_swap_b32 v250, v252
	v_permlane32_swap_b32 v251, v253
	s_nop 0
	global_store_dwordx4 v[54:55], v[250:253], off
	ds_read_b128 v[50:53], v249 offset:64
	v_pk_mul_f32 v[20:21], v[110:111], v[0:1] op_sel_hi:[1,0]
	s_waitcnt lgkmcnt(0)
	v_pk_mul_f32 v[20:21], v[50:51], v[20:21]
	v_pk_mul_f32 v[50:51], v[52:53], v[56:57]
	v_cvt_pk_bf16_f32 v250, v20, v21
	v_cvt_pk_bf16_f32 v251, v50, v51
	ds_read_b128 v[50:53], v249 offset:96
	v_pk_mul_f32 v[20:21], v[112:113], v[0:1] op_sel_hi:[1,0]
	v_pk_mul_f32 v[56:57], v[94:95], v[0:1] op_sel_hi:[1,0]
	s_waitcnt lgkmcnt(0)
	v_pk_mul_f32 v[20:21], v[50:51], v[20:21]
	v_pk_mul_f32 v[50:51], v[52:53], v[56:57]
	v_cvt_pk_bf16_f32 v252, v20, v21
	v_cvt_pk_bf16_f32 v253, v50, v51
	s_nop 1
	v_permlane32_swap_b32 v250, v252
	v_permlane32_swap_b32 v251, v253
	s_nop 0
	global_store_dwordx4 v[54:55], v[250:253], off offset:32
	ds_read_b128 v[50:53], v249 offset:128
	v_pk_mul_f32 v[20:21], v[102:103], v[0:1] op_sel_hi:[1,0]
	v_pk_mul_f32 v[56:57], v[96:97], v[0:1] op_sel_hi:[1,0]
	s_waitcnt lgkmcnt(0)
	v_pk_mul_f32 v[20:21], v[50:51], v[20:21]
	v_pk_mul_f32 v[50:51], v[52:53], v[56:57]
	v_cvt_pk_bf16_f32 v250, v20, v21
	v_cvt_pk_bf16_f32 v251, v50, v51
	ds_read_b128 v[50:53], v249 offset:160
	v_pk_mul_f32 v[20:21], v[104:105], v[0:1] op_sel_hi:[1,0]
	s_waitcnt lgkmcnt(0)
	v_pk_mul_f32 v[32:33], v[52:53], v[32:33]
	v_pk_mul_f32 v[20:21], v[50:51], v[20:21]
	s_nop 0
	v_cvt_pk_bf16_f32 v252, v20, v21
	v_cvt_pk_bf16_f32 v253, v32, v33
	s_nop 1
	v_permlane32_swap_b32 v250, v252
	v_permlane32_swap_b32 v251, v253
	s_nop 0
	global_store_dwordx4 v[54:55], v[250:253], off offset:64
	ds_read_b128 v[50:53], v249 offset:192
	v_pk_mul_f32 v[20:21], v[106:107], v[0:1] op_sel_hi:[1,0]
	v_pk_mul_f32 v[32:33], v[34:35], v[0:1] op_sel_hi:[1,0]
	s_waitcnt lgkmcnt(0)
	v_pk_mul_f32 v[20:21], v[50:51], v[20:21]
	v_pk_mul_f32 v[32:33], v[52:53], v[32:33]
	v_cvt_pk_bf16_f32 v250, v20, v21
	v_cvt_pk_bf16_f32 v251, v32, v33
	ds_read_b128 v[32:35], v249 offset:224
	v_pk_mul_f32 v[20:21], v[108:109], v[0:1] op_sel_hi:[1,0]
	s_waitcnt lgkmcnt(0)
	v_pk_mul_f32 v[20:21], v[20:21], v[32:33]
	v_pk_mul_f32 v[32:33], v[36:37], v[34:35]
	v_cvt_pk_bf16_f32 v252, v20, v21
	v_cvt_pk_bf16_f32 v253, v32, v33
	s_nop 1
	v_permlane32_swap_b32 v250, v252
	v_permlane32_swap_b32 v251, v253
	s_nop 0
	global_store_dwordx4 v[54:55], v[250:253], off offset:96
	ds_read_b128 v[32:35], v249 offset:256
	v_pk_mul_f32 v[20:21], v[46:47], v[0:1] op_sel_hi:[1,0]
	v_pk_mul_f32 v[36:37], v[38:39], v[0:1] op_sel_hi:[1,0]
	s_waitcnt lgkmcnt(0)
	v_pk_mul_f32 v[20:21], v[20:21], v[32:33]
	v_pk_mul_f32 v[32:33], v[36:37], v[34:35]
	v_cvt_pk_bf16_f32 v250, v20, v21
	v_cvt_pk_bf16_f32 v251, v32, v33
	ds_read_b128 v[32:35], v249 offset:288
	v_pk_mul_f32 v[20:21], v[48:49], v[0:1] op_sel_hi:[1,0]
	s_waitcnt lgkmcnt(0)
	v_pk_mul_f32 v[24:25], v[24:25], v[34:35]
	v_pk_mul_f32 v[20:21], v[20:21], v[32:33]
	s_nop 0
	v_cvt_pk_bf16_f32 v252, v20, v21
	v_cvt_pk_bf16_f32 v253, v24, v25
	s_nop 1
	v_permlane32_swap_b32 v250, v252
	v_permlane32_swap_b32 v251, v253
	s_nop 0
	global_store_dwordx4 v[54:55], v[250:253], off offset:128
	ds_read_b128 v[32:35], v249 offset:320
	v_pk_mul_f32 v[20:21], v[66:67], v[0:1] op_sel_hi:[1,0]
	v_pk_mul_f32 v[24:25], v[26:27], v[0:1] op_sel_hi:[1,0]
	s_waitcnt lgkmcnt(0)
	v_pk_mul_f32 v[20:21], v[20:21], v[32:33]
	v_pk_mul_f32 v[24:25], v[24:25], v[34:35]
	v_cvt_pk_bf16_f32 v250, v20, v21
	v_cvt_pk_bf16_f32 v251, v24, v25
	ds_read_b128 v[24:27], v249 offset:352
	v_pk_mul_f32 v[20:21], v[68:69], v[0:1] op_sel_hi:[1,0]
	s_waitcnt lgkmcnt(0)
	v_pk_mul_f32 v[20:21], v[20:21], v[24:25]
	v_pk_mul_f32 v[24:25], v[28:29], v[26:27]
	v_cvt_pk_bf16_f32 v252, v20, v21
	v_cvt_pk_bf16_f32 v253, v24, v25
	s_nop 1
	v_permlane32_swap_b32 v250, v252
	v_permlane32_swap_b32 v251, v253
	s_nop 0
	global_store_dwordx4 v[54:55], v[250:253], off offset:160
	ds_read_b128 v[24:27], v249 offset:384
	v_pk_mul_f32 v[20:21], v[40:41], v[0:1] op_sel_hi:[1,0]
	v_pk_mul_f32 v[28:29], v[30:31], v[0:1] op_sel_hi:[1,0]
	s_waitcnt lgkmcnt(0)
	v_pk_mul_f32 v[20:21], v[20:21], v[24:25]
	v_pk_mul_f32 v[24:25], v[28:29], v[26:27]
	v_cvt_pk_bf16_f32 v250, v20, v21
	v_cvt_pk_bf16_f32 v251, v24, v25
	ds_read_b128 v[24:27], v249 offset:416
	v_pk_mul_f32 v[20:21], v[42:43], v[0:1] op_sel_hi:[1,0]
	s_waitcnt lgkmcnt(0)
	v_pk_mul_f32 v[18:19], v[18:19], v[26:27]
	v_pk_mul_f32 v[20:21], v[20:21], v[24:25]
	v_pk_mul_f32 v[24:25], v[44:45], v[0:1] op_sel_hi:[1,0]
	v_cvt_pk_bf16_f32 v252, v20, v21
	v_cvt_pk_bf16_f32 v253, v18, v19
	s_nop 1
	v_permlane32_swap_b32 v250, v252
	v_permlane32_swap_b32 v251, v253
	s_nop 0
	global_store_dwordx4 v[54:55], v[250:253], off offset:192
	ds_read_b128 v[18:21], v249 offset:448
	s_waitcnt lgkmcnt(0)
	v_pk_mul_f32 v[18:19], v[24:25], v[18:19]
	v_pk_mul_f32 v[20:21], v[22:23], v[20:21]
	v_cvt_pk_bf16_f32 v250, v18, v19
	v_cvt_pk_bf16_f32 v251, v20, v21
	ds_read_b128 v[18:21], v249 offset:480
	v_pk_mul_f32 v[22:23], v[82:83], v[0:1] op_sel_hi:[1,0]
	v_pk_mul_f32 v[24:25], v[84:85], v[0:1] op_sel_hi:[1,0]
	s_waitcnt lgkmcnt(0)
	v_pk_mul_f32 v[18:19], v[22:23], v[18:19]
	v_pk_mul_f32 v[20:21], v[24:25], v[20:21]
	v_cvt_pk_bf16_f32 v252, v18, v19
	v_cvt_pk_bf16_f32 v253, v20, v21
	s_nop 1
	v_permlane32_swap_b32 v250, v252
	v_permlane32_swap_b32 v251, v253
	s_nop 0
	global_store_dwordx4 v[54:55], v[250:253], off offset:224
	s_branch .LBB0_331
